# S5 GLU GEMM epilogue: bias quads + y loads of 7 row groups hoisted, 8th group's loads issued after group 0 (on top of s3+rev5+prioB+s5c)
# speedup vs baseline: 1.0018x; 1.0018x over previous
.LBB0_2720:
	v_mov_b32_e32 v136, v0
	s_lshl_b32 s0, s22, 8
	s_add_i32 s0, s0, s50
	v_and_or_b32 v138, v136, 15, s0
	s_lshl_b32 s0, s18, 8
	v_lshrrev_b32_e32 v136, 2, v136
	v_and_or_b32 v136, v136, 12, s0
	v_or_b32_e32 v140, s51, v136
	v_ashrrev_i32_e32 v141, 31, v140
	v_lshl_add_u64 v[136:137], v[140:141], 2, s[8:9]
	v_readlane_b32 s56, v246, 17
	v_readlane_b32 s57, v246, 18
	v_lshlrev_b32_e32 v143, 10, v138
	v_lshl_add_u32 v143, v140, 1, v143
	global_load_dwordx4 v[152:155], v[136:137], off
	global_load_dwordx4 v[156:159], v[136:137], off offset:64
	global_load_dwordx4 v[160:163], v[136:137], off offset:512
	global_load_dwordx4 v[164:167], v[136:137], off offset:576
	global_load_dwordx2 v[168:169], v143, s[56:57]
	global_load_dwordx2 v[170:171], v143, s[56:57] offset:32
	global_load_dwordx2 v[172:173], v143, s[56:57] offset:256
	global_load_dwordx2 v[174:175], v143, s[56:57] offset:288
	s_add_u32 s58, s56, 0x4000
	s_addc_u32 s59, s57, 0
	global_load_dwordx2 v[176:177], v143, s[58:59]
	global_load_dwordx2 v[178:179], v143, s[58:59] offset:32
	global_load_dwordx2 v[180:181], v143, s[58:59] offset:256
	global_load_dwordx2 v[182:183], v143, s[58:59] offset:288
	s_add_u32 s58, s56, 0x8000
	s_addc_u32 s59, s57, 0
	global_load_dwordx2 v[184:185], v143, s[58:59]
	global_load_dwordx2 v[186:187], v143, s[58:59] offset:32
	global_load_dwordx2 v[188:189], v143, s[58:59] offset:256
	global_load_dwordx2 v[192:193], v143, s[58:59] offset:288
	s_add_u32 s58, s56, 0xc000
	s_addc_u32 s59, s57, 0
	global_load_dwordx2 v[194:195], v143, s[58:59]
	global_load_dwordx2 v[196:197], v143, s[58:59] offset:32
	global_load_dwordx2 v[198:199], v143, s[58:59] offset:256
	global_load_dwordx2 v[200:201], v143, s[58:59] offset:288
	s_add_u32 s58, s56, 0x20000
	s_addc_u32 s59, s57, 0
	global_load_dwordx2 v[202:203], v143, s[58:59]
	global_load_dwordx2 v[204:205], v143, s[58:59] offset:32
	global_load_dwordx2 v[206:207], v143, s[58:59] offset:256
	global_load_dwordx2 v[208:209], v143, s[58:59] offset:288
	s_add_u32 s58, s56, 0x24000
	s_addc_u32 s59, s57, 0
	global_load_dwordx2 v[210:211], v143, s[58:59]
	global_load_dwordx2 v[212:213], v143, s[58:59] offset:32
	global_load_dwordx2 v[214:215], v143, s[58:59] offset:256
	global_load_dwordx2 v[222:223], v143, s[58:59] offset:288
	s_add_u32 s58, s56, 0x28000
	s_addc_u32 s59, s57, 0
	global_load_dwordx2 v[224:225], v143, s[58:59]
	global_load_dwordx2 v[228:229], v143, s[58:59] offset:32
	global_load_dwordx2 v[232:233], v143, s[58:59] offset:256
	global_load_dwordx2 v[234:235], v143, s[58:59] offset:288
	s_waitcnt vmcnt(0)
	s_nop 0
	v_ashrrev_i32_e32 v139, 31, v138
	v_readlane_b32 s28, v246, 17
	v_lshlrev_b64 v[148:149], 10, v[138:139]
	v_readlane_b32 s29, v246, 18
	v_lshlrev_b64 v[150:151], 12, v[138:139]
	v_readlane_b32 s18, v246, 37
	v_readlane_b32 s19, v246, 38
	s_andn2_b64 vcc, exec, s[4:5]
	s_nop 0
	v_pk_add_f32 v[146:147], v[128:129], v[154:155]
	v_pk_add_f32 v[144:145], v[126:127], v[152:153]
	v_lshl_add_u64 v[128:129], s[28:29], 0, v[148:149]
	v_lshlrev_b64 v[126:127], 1, v[140:141]
	v_lshl_add_u64 v[128:129], v[128:129], 0, v[126:127]
	s_nop 0
	v_mul_f32_e32 v139, 0xbfb8aa3b, v144
	v_exp_f32_e32 v139, v139
	s_nop 0
	v_lshlrev_b32_e32 v148, 16, v168
	v_add_f32_e32 v139, 1.0, v139
	v_rcp_f32_e32 v144, v139
	v_mul_f32_e32 v139, 0xbfb8aa3b, v145
	v_exp_f32_e32 v139, v139
	v_and_b32_e32 v149, 0xffff0000, v168
	v_lshlrev_b32_e32 v140, 16, v169
	v_and_b32_e32 v141, 0xffff0000, v169
	v_add_f32_e32 v139, 1.0, v139
	v_rcp_f32_e32 v145, v139
	v_mul_f32_e32 v139, 0xbfb8aa3b, v146
	v_exp_f32_e32 v139, v139
	v_pk_mul_f32 v[144:145], v[144:145], v[148:149]
	s_nop 0
	v_cvt_pk_bf16_f32 v144, v144, v145
	v_add_f32_e32 v139, 1.0, v139
	v_rcp_f32_e32 v146, v139
	v_mul_f32_e32 v139, 0xbfb8aa3b, v147
	v_exp_f32_e32 v139, v139
	s_nop 0
	v_add_f32_e32 v139, 1.0, v139
	v_rcp_f32_e32 v147, v139
	s_nop 0
	v_pk_mul_f32 v[140:141], v[146:147], v[140:141]
	s_nop 0
	v_cvt_pk_bf16_f32 v145, v140, v141
	v_lshl_add_u64 v[140:141], s[18:19], 0, v[150:151]
	v_lshl_add_u64 v[140:141], v[140:141], 0, v[126:127]
	global_store_dwordx2 v[140:141], v[144:145], off offset:3072
	s_nop 0
	s_nop 0
	v_pk_add_f32 v[122:123], v[122:123], v[156:157]
	s_nop 0
	v_mul_f32_e32 v122, 0xbfb8aa3b, v122
	v_mul_f32_e32 v123, 0xbfb8aa3b, v123
	v_exp_f32_e32 v122, v122
	v_exp_f32_e32 v123, v123
	v_pk_add_f32 v[124:125], v[124:125], v[158:159]
	v_add_f32_e32 v122, 1.0, v122
	v_add_f32_e32 v123, 1.0, v123
	v_rcp_f32_e32 v122, v122
	v_rcp_f32_e32 v123, v123
	s_nop 0
	v_lshlrev_b32_e32 v146, 16, v170
	v_and_b32_e32 v147, 0xffff0000, v170
	v_pk_mul_f32 v[122:123], v[122:123], v[146:147]
	v_lshlrev_b32_e32 v144, 16, v171
	v_cvt_pk_bf16_f32 v122, v122, v123
	v_mul_f32_e32 v123, 0xbfb8aa3b, v124
	v_exp_f32_e32 v123, v123
	v_and_b32_e32 v145, 0xffff0000, v171
	v_add_f32_e32 v123, 1.0, v123
	v_rcp_f32_e32 v124, v123
	v_mul_f32_e32 v123, 0xbfb8aa3b, v125
	v_exp_f32_e32 v123, v123
	s_nop 0
	v_add_f32_e32 v123, 1.0, v123
	v_rcp_f32_e32 v125, v123
	s_nop 0
	v_pk_mul_f32 v[124:125], v[124:125], v[144:145]
	s_nop 0
	v_cvt_pk_bf16_f32 v123, v124, v125
	global_store_dwordx2 v[140:141], v[122:123], off offset:3104
	s_nop 0
	s_nop 0
	v_pk_add_f32 v[118:119], v[118:119], v[160:161]
	s_nop 0
	v_mul_f32_e32 v118, 0xbfb8aa3b, v118
	v_mul_f32_e32 v119, 0xbfb8aa3b, v119
	v_exp_f32_e32 v118, v118
	v_exp_f32_e32 v119, v119
	v_pk_add_f32 v[120:121], v[120:121], v[162:163]
	v_add_f32_e32 v118, 1.0, v118
	v_add_f32_e32 v119, 1.0, v119
	v_rcp_f32_e32 v118, v118
	v_rcp_f32_e32 v119, v119
	s_nop 0
	v_lshlrev_b32_e32 v124, 16, v172
	v_and_b32_e32 v125, 0xffff0000, v172
	v_pk_mul_f32 v[118:119], v[118:119], v[124:125]
	v_lshlrev_b32_e32 v122, 16, v173
	v_cvt_pk_bf16_f32 v118, v118, v119
	v_mul_f32_e32 v119, 0xbfb8aa3b, v120
	v_exp_f32_e32 v119, v119
	v_and_b32_e32 v123, 0xffff0000, v173
	v_add_f32_e32 v119, 1.0, v119
	v_rcp_f32_e32 v120, v119
	v_mul_f32_e32 v119, 0xbfb8aa3b, v121
	v_exp_f32_e32 v119, v119
	s_nop 0
	v_add_f32_e32 v119, 1.0, v119
	v_rcp_f32_e32 v121, v119
	s_nop 0
	v_pk_mul_f32 v[120:121], v[120:121], v[122:123]
	s_nop 0
	v_cvt_pk_bf16_f32 v119, v120, v121
	global_store_dwordx2 v[140:141], v[118:119], off offset:3328
	s_nop 0
	s_nop 0
	v_pk_add_f32 v[114:115], v[114:115], v[164:165]
	s_nop 0
	v_mul_f32_e32 v114, 0xbfb8aa3b, v114
	v_mul_f32_e32 v115, 0xbfb8aa3b, v115
	v_exp_f32_e32 v114, v114
	v_exp_f32_e32 v115, v115
	v_pk_add_f32 v[116:117], v[116:117], v[166:167]
	v_add_f32_e32 v114, 1.0, v114
	v_add_f32_e32 v115, 1.0, v115
	v_rcp_f32_e32 v114, v114
	v_rcp_f32_e32 v115, v115
	s_nop 0
	v_lshlrev_b32_e32 v120, 16, v174
	v_and_b32_e32 v121, 0xffff0000, v174
	v_pk_mul_f32 v[114:115], v[114:115], v[120:121]
	v_lshlrev_b32_e32 v118, 16, v175
	v_cvt_pk_bf16_f32 v114, v114, v115
	v_mul_f32_e32 v115, 0xbfb8aa3b, v116
	v_exp_f32_e32 v115, v115
	v_and_b32_e32 v119, 0xffff0000, v175
	v_add_f32_e32 v115, 1.0, v115
	v_rcp_f32_e32 v116, v115
	v_mul_f32_e32 v115, 0xbfb8aa3b, v117
	v_exp_f32_e32 v115, v115
	s_nop 0
	v_add_f32_e32 v115, 1.0, v115
	v_rcp_f32_e32 v117, v115
	s_nop 0
	v_pk_mul_f32 v[116:117], v[116:117], v[118:119]
	s_nop 0
	v_cvt_pk_bf16_f32 v115, v116, v117
	global_store_dwordx2 v[140:141], v[114:115], off offset:3360
	s_add_u32 s58, s56, 0x2c000
	s_addc_u32 s59, s57, 0
	global_load_dwordx2 v[168:169], v143, s[58:59]
	global_load_dwordx2 v[170:171], v143, s[58:59] offset:32
	global_load_dwordx2 v[172:173], v143, s[58:59] offset:256
	global_load_dwordx2 v[174:175], v143, s[58:59] offset:288
	s_nop 0
	v_or_b32_e32 v114, 16, v138
	v_ashrrev_i32_e32 v115, 31, v114
	v_lshlrev_b64 v[120:121], 10, v[114:115]
	v_lshlrev_b64 v[114:115], 12, v[114:115]
	s_nop 0
	v_pk_add_f32 v[116:117], v[110:111], v[152:153]
	v_lshl_add_u64 v[110:111], s[28:29], 0, v[120:121]
	v_lshl_add_u64 v[110:111], v[110:111], 0, v[126:127]
	v_pk_add_f32 v[112:113], v[112:113], v[154:155]
	s_nop 0
	v_mul_f32_e32 v116, 0xbfb8aa3b, v116
	v_mul_f32_e32 v117, 0xbfb8aa3b, v117
	v_mul_f32_e32 v112, 0xbfb8aa3b, v112
	v_mul_f32_e32 v113, 0xbfb8aa3b, v113
	v_exp_f32_e32 v116, v116
	v_exp_f32_e32 v117, v117
	v_exp_f32_e32 v112, v112
	v_exp_f32_e32 v113, v113
	v_add_f32_e32 v116, 1.0, v116
	v_add_f32_e32 v117, 1.0, v117
	v_add_f32_e32 v112, 1.0, v112
	v_add_f32_e32 v113, 1.0, v113
	v_rcp_f32_e32 v116, v116
	v_rcp_f32_e32 v117, v117
	v_rcp_f32_e32 v112, v112
	v_rcp_f32_e32 v113, v113
	s_nop 0
	v_lshlrev_b32_e32 v120, 16, v176
	v_and_b32_e32 v121, 0xffff0000, v176
	v_lshlrev_b32_e32 v118, 16, v177
	v_and_b32_e32 v119, 0xffff0000, v177
	v_pk_mul_f32 v[116:117], v[116:117], v[120:121]
	v_pk_mul_f32 v[112:113], v[112:113], v[118:119]
	v_cvt_pk_bf16_f32 v116, v116, v117
	v_cvt_pk_bf16_f32 v117, v112, v113
	v_lshl_add_u64 v[112:113], s[18:19], 0, v[114:115]
	v_lshl_add_u64 v[112:113], v[112:113], 0, v[126:127]
	global_store_dwordx2 v[112:113], v[116:117], off offset:3072
	s_nop 0
	s_nop 0
	v_pk_add_f32 v[106:107], v[106:107], v[156:157]
	s_nop 0
	v_mul_f32_e32 v106, 0xbfb8aa3b, v106
	v_mul_f32_e32 v107, 0xbfb8aa3b, v107
	v_exp_f32_e32 v106, v106
	v_exp_f32_e32 v107, v107
	v_pk_add_f32 v[108:109], v[108:109], v[158:159]
	v_add_f32_e32 v106, 1.0, v106
	v_add_f32_e32 v107, 1.0, v107
	v_rcp_f32_e32 v106, v106
	v_rcp_f32_e32 v107, v107
	s_nop 0
	v_lshlrev_b32_e32 v116, 16, v178
	v_and_b32_e32 v117, 0xffff0000, v178
	v_pk_mul_f32 v[106:107], v[106:107], v[116:117]
	v_lshlrev_b32_e32 v114, 16, v179
	v_cvt_pk_bf16_f32 v106, v106, v107
	v_mul_f32_e32 v107, 0xbfb8aa3b, v108
	v_exp_f32_e32 v107, v107
	v_and_b32_e32 v115, 0xffff0000, v179
	v_add_f32_e32 v107, 1.0, v107
	v_rcp_f32_e32 v108, v107
	v_mul_f32_e32 v107, 0xbfb8aa3b, v109
	v_exp_f32_e32 v107, v107
	s_nop 0
	v_add_f32_e32 v107, 1.0, v107
	v_rcp_f32_e32 v109, v107
	s_nop 0
	v_pk_mul_f32 v[108:109], v[108:109], v[114:115]
	s_nop 0
	v_cvt_pk_bf16_f32 v107, v108, v109
	global_store_dwordx2 v[112:113], v[106:107], off offset:3104
	s_nop 0
	s_nop 0
	v_pk_add_f32 v[102:103], v[102:103], v[160:161]
	s_nop 0
	v_mul_f32_e32 v102, 0xbfb8aa3b, v102
	v_mul_f32_e32 v103, 0xbfb8aa3b, v103
	v_exp_f32_e32 v102, v102
	v_exp_f32_e32 v103, v103
	v_pk_add_f32 v[104:105], v[104:105], v[162:163]
	v_add_f32_e32 v102, 1.0, v102
	v_add_f32_e32 v103, 1.0, v103
	v_rcp_f32_e32 v102, v102
	v_rcp_f32_e32 v103, v103
	s_nop 0
	v_lshlrev_b32_e32 v108, 16, v180
	v_and_b32_e32 v109, 0xffff0000, v180
	v_pk_mul_f32 v[102:103], v[102:103], v[108:109]
	v_lshlrev_b32_e32 v106, 16, v181
	v_cvt_pk_bf16_f32 v102, v102, v103
	v_mul_f32_e32 v103, 0xbfb8aa3b, v104
	v_exp_f32_e32 v103, v103
	v_and_b32_e32 v107, 0xffff0000, v181
	v_add_f32_e32 v103, 1.0, v103
	v_rcp_f32_e32 v104, v103
	v_mul_f32_e32 v103, 0xbfb8aa3b, v105
	v_exp_f32_e32 v103, v103
	s_nop 0
	v_add_f32_e32 v103, 1.0, v103
	v_rcp_f32_e32 v105, v103
	s_nop 0
	v_pk_mul_f32 v[104:105], v[104:105], v[106:107]
	s_nop 0
	v_cvt_pk_bf16_f32 v103, v104, v105
	global_store_dwordx2 v[112:113], v[102:103], off offset:3328
	s_nop 0
	s_nop 0
	v_pk_add_f32 v[98:99], v[98:99], v[164:165]
	s_nop 0
	v_mul_f32_e32 v98, 0xbfb8aa3b, v98
	v_mul_f32_e32 v99, 0xbfb8aa3b, v99
	v_exp_f32_e32 v98, v98
	v_exp_f32_e32 v99, v99
	v_pk_add_f32 v[100:101], v[100:101], v[166:167]
	v_add_f32_e32 v98, 1.0, v98
	v_add_f32_e32 v99, 1.0, v99
	v_rcp_f32_e32 v98, v98
	v_rcp_f32_e32 v99, v99
	s_nop 0
	v_lshlrev_b32_e32 v104, 16, v182
	v_and_b32_e32 v105, 0xffff0000, v182
	v_pk_mul_f32 v[98:99], v[98:99], v[104:105]
	v_lshlrev_b32_e32 v102, 16, v183
	v_cvt_pk_bf16_f32 v98, v98, v99
	v_mul_f32_e32 v99, 0xbfb8aa3b, v100
	v_exp_f32_e32 v99, v99
	v_and_b32_e32 v103, 0xffff0000, v183
	v_add_f32_e32 v99, 1.0, v99
	v_rcp_f32_e32 v100, v99
	v_mul_f32_e32 v99, 0xbfb8aa3b, v101
	v_exp_f32_e32 v99, v99
	s_nop 0
	v_add_f32_e32 v99, 1.0, v99
	v_rcp_f32_e32 v101, v99
	s_nop 0
	v_pk_mul_f32 v[100:101], v[100:101], v[102:103]
	s_nop 0
	v_cvt_pk_bf16_f32 v99, v100, v101
	global_store_dwordx2 v[112:113], v[98:99], off offset:3360
	s_nop 0
	v_or_b32_e32 v98, 32, v138
	v_ashrrev_i32_e32 v99, 31, v98
	v_lshlrev_b64 v[104:105], 10, v[98:99]
	v_lshlrev_b64 v[98:99], 12, v[98:99]
	s_nop 0
	v_pk_add_f32 v[100:101], v[94:95], v[152:153]
	v_lshl_add_u64 v[94:95], s[28:29], 0, v[104:105]
	v_lshl_add_u64 v[94:95], v[94:95], 0, v[126:127]
	v_pk_add_f32 v[96:97], v[96:97], v[154:155]
	s_nop 0
	v_mul_f32_e32 v100, 0xbfb8aa3b, v100
	v_mul_f32_e32 v101, 0xbfb8aa3b, v101
	v_mul_f32_e32 v96, 0xbfb8aa3b, v96
	v_mul_f32_e32 v97, 0xbfb8aa3b, v97
	v_exp_f32_e32 v100, v100
	v_exp_f32_e32 v101, v101
	v_exp_f32_e32 v96, v96
	v_exp_f32_e32 v97, v97
	v_add_f32_e32 v100, 1.0, v100
	v_add_f32_e32 v101, 1.0, v101
	v_add_f32_e32 v96, 1.0, v96
	v_add_f32_e32 v97, 1.0, v97
	v_rcp_f32_e32 v100, v100
	v_rcp_f32_e32 v101, v101
	v_rcp_f32_e32 v96, v96
	v_rcp_f32_e32 v97, v97
	s_nop 0
	v_lshlrev_b32_e32 v104, 16, v184
	v_and_b32_e32 v105, 0xffff0000, v184
	v_lshlrev_b32_e32 v102, 16, v185
	v_and_b32_e32 v103, 0xffff0000, v185
	v_pk_mul_f32 v[100:101], v[100:101], v[104:105]
	v_pk_mul_f32 v[96:97], v[96:97], v[102:103]
	v_cvt_pk_bf16_f32 v100, v100, v101
	v_cvt_pk_bf16_f32 v101, v96, v97
	v_lshl_add_u64 v[96:97], s[18:19], 0, v[98:99]
	v_lshl_add_u64 v[96:97], v[96:97], 0, v[126:127]
	global_store_dwordx2 v[96:97], v[100:101], off offset:3072
	s_nop 0
	s_nop 0
	v_pk_add_f32 v[90:91], v[90:91], v[156:157]
	s_nop 0
	v_mul_f32_e32 v90, 0xbfb8aa3b, v90
	v_mul_f32_e32 v91, 0xbfb8aa3b, v91
	v_exp_f32_e32 v90, v90
	v_exp_f32_e32 v91, v91
	v_pk_add_f32 v[92:93], v[92:93], v[158:159]
	v_add_f32_e32 v90, 1.0, v90
	v_add_f32_e32 v91, 1.0, v91
	v_rcp_f32_e32 v90, v90
	v_rcp_f32_e32 v91, v91
	s_nop 0
	v_lshlrev_b32_e32 v100, 16, v186
	v_and_b32_e32 v101, 0xffff0000, v186
	v_pk_mul_f32 v[90:91], v[90:91], v[100:101]
	v_lshlrev_b32_e32 v98, 16, v187
	v_cvt_pk_bf16_f32 v90, v90, v91
	v_mul_f32_e32 v91, 0xbfb8aa3b, v92
	v_exp_f32_e32 v91, v91
	v_and_b32_e32 v99, 0xffff0000, v187
	v_add_f32_e32 v91, 1.0, v91
	v_rcp_f32_e32 v92, v91
	v_mul_f32_e32 v91, 0xbfb8aa3b, v93
	v_exp_f32_e32 v91, v91
	s_nop 0
	v_add_f32_e32 v91, 1.0, v91
	v_rcp_f32_e32 v93, v91
	s_nop 0
	v_pk_mul_f32 v[92:93], v[92:93], v[98:99]
	s_nop 0
	v_cvt_pk_bf16_f32 v91, v92, v93
	global_store_dwordx2 v[96:97], v[90:91], off offset:3104
	s_nop 0
	s_nop 0
	v_pk_add_f32 v[86:87], v[86:87], v[160:161]
	s_nop 0
	v_mul_f32_e32 v86, 0xbfb8aa3b, v86
	v_mul_f32_e32 v87, 0xbfb8aa3b, v87
	v_exp_f32_e32 v86, v86
	v_exp_f32_e32 v87, v87
	v_pk_add_f32 v[88:89], v[88:89], v[162:163]
	v_add_f32_e32 v86, 1.0, v86
	v_add_f32_e32 v87, 1.0, v87
	v_rcp_f32_e32 v86, v86
	v_rcp_f32_e32 v87, v87
	s_nop 0
	v_lshlrev_b32_e32 v92, 16, v188
	v_and_b32_e32 v93, 0xffff0000, v188
	v_pk_mul_f32 v[86:87], v[86:87], v[92:93]
	v_lshlrev_b32_e32 v90, 16, v189
	v_cvt_pk_bf16_f32 v86, v86, v87
	v_mul_f32_e32 v87, 0xbfb8aa3b, v88
	v_exp_f32_e32 v87, v87
	v_and_b32_e32 v91, 0xffff0000, v189
	v_add_f32_e32 v87, 1.0, v87
	v_rcp_f32_e32 v88, v87
	v_mul_f32_e32 v87, 0xbfb8aa3b, v89
	v_exp_f32_e32 v87, v87
	s_nop 0
	v_add_f32_e32 v87, 1.0, v87
	v_rcp_f32_e32 v89, v87
	s_nop 0
	v_pk_mul_f32 v[88:89], v[88:89], v[90:91]
	s_nop 0
	v_cvt_pk_bf16_f32 v87, v88, v89
	global_store_dwordx2 v[96:97], v[86:87], off offset:3328
	s_nop 0
	s_nop 0
	v_pk_add_f32 v[82:83], v[82:83], v[164:165]
	s_nop 0
	v_mul_f32_e32 v82, 0xbfb8aa3b, v82
	v_mul_f32_e32 v83, 0xbfb8aa3b, v83
	v_exp_f32_e32 v82, v82
	v_exp_f32_e32 v83, v83
	v_pk_add_f32 v[84:85], v[84:85], v[166:167]
	v_add_f32_e32 v82, 1.0, v82
	v_add_f32_e32 v83, 1.0, v83
	v_rcp_f32_e32 v82, v82
	v_rcp_f32_e32 v83, v83
	s_nop 0
	v_lshlrev_b32_e32 v88, 16, v192
	v_and_b32_e32 v89, 0xffff0000, v192
	v_pk_mul_f32 v[82:83], v[82:83], v[88:89]
	v_lshlrev_b32_e32 v86, 16, v193
	v_cvt_pk_bf16_f32 v82, v82, v83
	v_mul_f32_e32 v83, 0xbfb8aa3b, v84
	v_exp_f32_e32 v83, v83
	v_and_b32_e32 v87, 0xffff0000, v193
	v_add_f32_e32 v83, 1.0, v83
	v_rcp_f32_e32 v84, v83
	v_mul_f32_e32 v83, 0xbfb8aa3b, v85
	v_exp_f32_e32 v83, v83
	s_nop 0
	v_add_f32_e32 v83, 1.0, v83
	v_rcp_f32_e32 v85, v83
	s_nop 0
	v_pk_mul_f32 v[84:85], v[84:85], v[86:87]
	s_nop 0
	v_cvt_pk_bf16_f32 v83, v84, v85
	global_store_dwordx2 v[96:97], v[82:83], off offset:3360
	s_nop 0
	v_or_b32_e32 v82, 48, v138
	v_ashrrev_i32_e32 v83, 31, v82
	v_lshlrev_b64 v[88:89], 10, v[82:83]
	v_lshlrev_b64 v[82:83], 12, v[82:83]
	s_nop 0
	v_pk_add_f32 v[84:85], v[78:79], v[152:153]
	v_lshl_add_u64 v[78:79], s[28:29], 0, v[88:89]
	v_lshl_add_u64 v[78:79], v[78:79], 0, v[126:127]
	v_pk_add_f32 v[80:81], v[80:81], v[154:155]
	s_nop 0
	v_mul_f32_e32 v84, 0xbfb8aa3b, v84
	v_mul_f32_e32 v85, 0xbfb8aa3b, v85
	v_mul_f32_e32 v80, 0xbfb8aa3b, v80
	v_mul_f32_e32 v81, 0xbfb8aa3b, v81
	v_exp_f32_e32 v84, v84
	v_exp_f32_e32 v85, v85
	v_exp_f32_e32 v80, v80
	v_exp_f32_e32 v81, v81
	v_add_f32_e32 v84, 1.0, v84
	v_add_f32_e32 v85, 1.0, v85
	v_add_f32_e32 v80, 1.0, v80
	v_add_f32_e32 v81, 1.0, v81
	v_rcp_f32_e32 v84, v84
	v_rcp_f32_e32 v85, v85
	v_rcp_f32_e32 v80, v80
	v_rcp_f32_e32 v81, v81
	s_nop 0
	v_lshlrev_b32_e32 v88, 16, v194
	v_and_b32_e32 v89, 0xffff0000, v194
	v_lshlrev_b32_e32 v86, 16, v195
	v_and_b32_e32 v87, 0xffff0000, v195
	v_pk_mul_f32 v[84:85], v[84:85], v[88:89]
	v_pk_mul_f32 v[80:81], v[80:81], v[86:87]
	v_cvt_pk_bf16_f32 v84, v84, v85
	v_cvt_pk_bf16_f32 v85, v80, v81
	v_lshl_add_u64 v[80:81], s[18:19], 0, v[82:83]
	v_lshl_add_u64 v[80:81], v[80:81], 0, v[126:127]
	global_store_dwordx2 v[80:81], v[84:85], off offset:3072
	s_nop 0
	s_nop 0
	v_pk_add_f32 v[74:75], v[74:75], v[156:157]
	s_nop 0
	v_mul_f32_e32 v74, 0xbfb8aa3b, v74
	v_mul_f32_e32 v75, 0xbfb8aa3b, v75
	v_exp_f32_e32 v74, v74
	v_exp_f32_e32 v75, v75
	v_pk_add_f32 v[76:77], v[76:77], v[158:159]
	v_add_f32_e32 v74, 1.0, v74
	v_add_f32_e32 v75, 1.0, v75
	v_rcp_f32_e32 v74, v74
	v_rcp_f32_e32 v75, v75
	s_nop 0
	v_lshlrev_b32_e32 v84, 16, v196
	v_and_b32_e32 v85, 0xffff0000, v196
	v_pk_mul_f32 v[74:75], v[74:75], v[84:85]
	v_lshlrev_b32_e32 v82, 16, v197
	v_cvt_pk_bf16_f32 v74, v74, v75
	v_mul_f32_e32 v75, 0xbfb8aa3b, v76
	v_exp_f32_e32 v75, v75
	v_and_b32_e32 v83, 0xffff0000, v197
	v_add_f32_e32 v75, 1.0, v75
	v_rcp_f32_e32 v76, v75
	v_mul_f32_e32 v75, 0xbfb8aa3b, v77
	v_exp_f32_e32 v75, v75
	s_nop 0
	v_add_f32_e32 v75, 1.0, v75
	v_rcp_f32_e32 v77, v75
	s_nop 0
	v_pk_mul_f32 v[76:77], v[76:77], v[82:83]
	s_nop 0
	v_cvt_pk_bf16_f32 v75, v76, v77
	global_store_dwordx2 v[80:81], v[74:75], off offset:3104
	s_nop 0
	s_nop 0
	v_pk_add_f32 v[70:71], v[70:71], v[160:161]
	s_nop 0
	v_mul_f32_e32 v70, 0xbfb8aa3b, v70
	v_mul_f32_e32 v71, 0xbfb8aa3b, v71
	v_exp_f32_e32 v70, v70
	v_exp_f32_e32 v71, v71
	v_pk_add_f32 v[72:73], v[72:73], v[162:163]
	v_add_f32_e32 v70, 1.0, v70
	v_add_f32_e32 v71, 1.0, v71
	v_rcp_f32_e32 v70, v70
	v_rcp_f32_e32 v71, v71
	s_nop 0
	v_lshlrev_b32_e32 v76, 16, v198
	v_and_b32_e32 v77, 0xffff0000, v198
	v_pk_mul_f32 v[70:71], v[70:71], v[76:77]
	v_lshlrev_b32_e32 v74, 16, v199
	v_cvt_pk_bf16_f32 v70, v70, v71
	v_mul_f32_e32 v71, 0xbfb8aa3b, v72
	v_exp_f32_e32 v71, v71
	v_and_b32_e32 v75, 0xffff0000, v199
	v_add_f32_e32 v71, 1.0, v71
	v_rcp_f32_e32 v72, v71
	v_mul_f32_e32 v71, 0xbfb8aa3b, v73
	v_exp_f32_e32 v71, v71
	s_nop 0
	v_add_f32_e32 v71, 1.0, v71
	v_rcp_f32_e32 v73, v71
	s_nop 0
	v_pk_mul_f32 v[72:73], v[72:73], v[74:75]
	s_nop 0
	v_cvt_pk_bf16_f32 v71, v72, v73
	global_store_dwordx2 v[80:81], v[70:71], off offset:3328
	s_nop 0
	s_nop 0
	v_pk_add_f32 v[66:67], v[66:67], v[164:165]
	s_nop 0
	v_mul_f32_e32 v66, 0xbfb8aa3b, v66
	v_mul_f32_e32 v67, 0xbfb8aa3b, v67
	v_exp_f32_e32 v66, v66
	v_exp_f32_e32 v67, v67
	v_pk_add_f32 v[68:69], v[68:69], v[166:167]
	v_add_f32_e32 v66, 1.0, v66
	v_add_f32_e32 v67, 1.0, v67
	v_rcp_f32_e32 v66, v66
	v_rcp_f32_e32 v67, v67
	s_nop 0
	v_lshlrev_b32_e32 v72, 16, v200
	v_and_b32_e32 v73, 0xffff0000, v200
	v_pk_mul_f32 v[66:67], v[66:67], v[72:73]
	v_lshlrev_b32_e32 v70, 16, v201
	v_cvt_pk_bf16_f32 v66, v66, v67
	v_mul_f32_e32 v67, 0xbfb8aa3b, v68
	v_exp_f32_e32 v67, v67
	v_and_b32_e32 v71, 0xffff0000, v201
	v_add_f32_e32 v67, 1.0, v67
	v_rcp_f32_e32 v68, v67
	v_mul_f32_e32 v67, 0xbfb8aa3b, v69
	v_exp_f32_e32 v67, v67
	s_nop 0
	v_add_f32_e32 v67, 1.0, v67
	v_rcp_f32_e32 v69, v67
	s_nop 0
	v_pk_mul_f32 v[68:69], v[68:69], v[70:71]
	s_nop 0
	v_cvt_pk_bf16_f32 v67, v68, v69
	global_store_dwordx2 v[80:81], v[66:67], off offset:3360
	s_nop 0
	v_add_u32_e32 v66, 0x80, v138
	v_ashrrev_i32_e32 v67, 31, v66
	v_lshlrev_b64 v[72:73], 10, v[66:67]
	v_lshlrev_b64 v[66:67], 12, v[66:67]
	s_nop 0
	v_pk_add_f32 v[68:69], v[62:63], v[152:153]
	v_lshl_add_u64 v[62:63], s[28:29], 0, v[72:73]
	v_lshl_add_u64 v[62:63], v[62:63], 0, v[126:127]
	v_pk_add_f32 v[64:65], v[64:65], v[154:155]
	s_nop 0
	v_mul_f32_e32 v68, 0xbfb8aa3b, v68
	v_mul_f32_e32 v69, 0xbfb8aa3b, v69
	v_mul_f32_e32 v64, 0xbfb8aa3b, v64
	v_mul_f32_e32 v65, 0xbfb8aa3b, v65
	v_exp_f32_e32 v68, v68
	v_exp_f32_e32 v69, v69
	v_exp_f32_e32 v64, v64
	v_exp_f32_e32 v65, v65
	v_add_f32_e32 v68, 1.0, v68
	v_add_f32_e32 v69, 1.0, v69
	v_add_f32_e32 v64, 1.0, v64
	v_add_f32_e32 v65, 1.0, v65
	v_rcp_f32_e32 v68, v68
	v_rcp_f32_e32 v69, v69
	v_rcp_f32_e32 v64, v64
	v_rcp_f32_e32 v65, v65
	s_nop 0
	v_lshlrev_b32_e32 v72, 16, v202
	v_and_b32_e32 v73, 0xffff0000, v202
	v_lshlrev_b32_e32 v70, 16, v203
	v_and_b32_e32 v71, 0xffff0000, v203
	v_pk_mul_f32 v[68:69], v[68:69], v[72:73]
	v_pk_mul_f32 v[64:65], v[64:65], v[70:71]
	v_cvt_pk_bf16_f32 v68, v68, v69
	v_cvt_pk_bf16_f32 v69, v64, v65
	v_lshl_add_u64 v[64:65], s[18:19], 0, v[66:67]
	v_lshl_add_u64 v[64:65], v[64:65], 0, v[126:127]
	global_store_dwordx2 v[64:65], v[68:69], off offset:3072
	s_nop 0
	s_nop 0
	v_pk_add_f32 v[58:59], v[58:59], v[156:157]
	s_nop 0
	v_mul_f32_e32 v58, 0xbfb8aa3b, v58
	v_mul_f32_e32 v59, 0xbfb8aa3b, v59
	v_exp_f32_e32 v58, v58
	v_exp_f32_e32 v59, v59
	v_pk_add_f32 v[60:61], v[60:61], v[158:159]
	v_add_f32_e32 v58, 1.0, v58
	v_add_f32_e32 v59, 1.0, v59
	v_rcp_f32_e32 v58, v58
	v_rcp_f32_e32 v59, v59
	s_nop 0
	v_lshlrev_b32_e32 v68, 16, v204
	v_and_b32_e32 v69, 0xffff0000, v204
	v_pk_mul_f32 v[58:59], v[58:59], v[68:69]
	v_lshlrev_b32_e32 v66, 16, v205
	v_cvt_pk_bf16_f32 v58, v58, v59
	v_mul_f32_e32 v59, 0xbfb8aa3b, v60
	v_exp_f32_e32 v59, v59
	v_and_b32_e32 v67, 0xffff0000, v205
	v_add_f32_e32 v59, 1.0, v59
	v_rcp_f32_e32 v60, v59
	v_mul_f32_e32 v59, 0xbfb8aa3b, v61
	v_exp_f32_e32 v59, v59
	s_nop 0
	v_add_f32_e32 v59, 1.0, v59
	v_rcp_f32_e32 v61, v59
	s_nop 0
	v_pk_mul_f32 v[60:61], v[60:61], v[66:67]
	s_nop 0
	v_cvt_pk_bf16_f32 v59, v60, v61
	global_store_dwordx2 v[64:65], v[58:59], off offset:3104
	s_nop 0
	s_nop 0
	v_pk_add_f32 v[54:55], v[54:55], v[160:161]
	s_nop 0
	v_mul_f32_e32 v54, 0xbfb8aa3b, v54
	v_mul_f32_e32 v55, 0xbfb8aa3b, v55
	v_exp_f32_e32 v54, v54
	v_exp_f32_e32 v55, v55
	v_pk_add_f32 v[56:57], v[56:57], v[162:163]
	v_add_f32_e32 v54, 1.0, v54
	v_add_f32_e32 v55, 1.0, v55
	v_rcp_f32_e32 v54, v54
	v_rcp_f32_e32 v55, v55
	s_nop 0
	v_lshlrev_b32_e32 v60, 16, v206
	v_and_b32_e32 v61, 0xffff0000, v206
	v_pk_mul_f32 v[54:55], v[54:55], v[60:61]
	v_lshlrev_b32_e32 v58, 16, v207
	v_cvt_pk_bf16_f32 v54, v54, v55
	v_mul_f32_e32 v55, 0xbfb8aa3b, v56
	v_exp_f32_e32 v55, v55
	v_and_b32_e32 v59, 0xffff0000, v207
	v_add_f32_e32 v55, 1.0, v55
	v_rcp_f32_e32 v56, v55
	v_mul_f32_e32 v55, 0xbfb8aa3b, v57
	v_exp_f32_e32 v55, v55
	s_nop 0
	v_add_f32_e32 v55, 1.0, v55
	v_rcp_f32_e32 v57, v55
	s_nop 0
	v_pk_mul_f32 v[56:57], v[56:57], v[58:59]
	s_nop 0
	v_cvt_pk_bf16_f32 v55, v56, v57
	global_store_dwordx2 v[64:65], v[54:55], off offset:3328
	s_nop 0
	s_nop 0
	v_pk_add_f32 v[50:51], v[50:51], v[164:165]
	s_nop 0
	v_mul_f32_e32 v50, 0xbfb8aa3b, v50
	v_mul_f32_e32 v51, 0xbfb8aa3b, v51
	v_exp_f32_e32 v50, v50
	v_exp_f32_e32 v51, v51
	v_pk_add_f32 v[52:53], v[52:53], v[166:167]
	v_add_f32_e32 v50, 1.0, v50
	v_add_f32_e32 v51, 1.0, v51
	v_rcp_f32_e32 v50, v50
	v_rcp_f32_e32 v51, v51
	s_nop 0
	v_lshlrev_b32_e32 v56, 16, v208
	v_and_b32_e32 v57, 0xffff0000, v208
	v_pk_mul_f32 v[50:51], v[50:51], v[56:57]
	v_lshlrev_b32_e32 v54, 16, v209
	v_cvt_pk_bf16_f32 v50, v50, v51
	v_mul_f32_e32 v51, 0xbfb8aa3b, v52
	v_exp_f32_e32 v51, v51
	v_and_b32_e32 v55, 0xffff0000, v209
	v_add_f32_e32 v51, 1.0, v51
	v_rcp_f32_e32 v52, v51
	v_mul_f32_e32 v51, 0xbfb8aa3b, v53
	v_exp_f32_e32 v51, v51
	s_nop 0
	v_add_f32_e32 v51, 1.0, v51
	v_rcp_f32_e32 v53, v51
	s_nop 0
	v_pk_mul_f32 v[52:53], v[52:53], v[54:55]
	s_nop 0
	v_cvt_pk_bf16_f32 v51, v52, v53
	global_store_dwordx2 v[64:65], v[50:51], off offset:3360
	s_nop 0
	v_add_u32_e32 v50, 0x90, v138
	v_ashrrev_i32_e32 v51, 31, v50
	v_lshlrev_b64 v[56:57], 10, v[50:51]
	v_lshlrev_b64 v[50:51], 12, v[50:51]
	s_nop 0
	v_pk_add_f32 v[52:53], v[46:47], v[152:153]
	v_lshl_add_u64 v[46:47], s[28:29], 0, v[56:57]
	v_lshl_add_u64 v[46:47], v[46:47], 0, v[126:127]
	v_pk_add_f32 v[48:49], v[48:49], v[154:155]
	s_nop 0
	v_mul_f32_e32 v52, 0xbfb8aa3b, v52
	v_mul_f32_e32 v53, 0xbfb8aa3b, v53
	v_mul_f32_e32 v48, 0xbfb8aa3b, v48
	v_mul_f32_e32 v49, 0xbfb8aa3b, v49
	v_exp_f32_e32 v52, v52
	v_exp_f32_e32 v53, v53
	v_exp_f32_e32 v48, v48
	v_exp_f32_e32 v49, v49
	v_add_f32_e32 v52, 1.0, v52
	v_add_f32_e32 v53, 1.0, v53
	v_add_f32_e32 v48, 1.0, v48
	v_add_f32_e32 v49, 1.0, v49
	v_rcp_f32_e32 v52, v52
	v_rcp_f32_e32 v53, v53
	v_rcp_f32_e32 v48, v48
	v_rcp_f32_e32 v49, v49
	s_nop 0
	v_lshlrev_b32_e32 v56, 16, v210
	v_and_b32_e32 v57, 0xffff0000, v210
	v_lshlrev_b32_e32 v54, 16, v211
	v_and_b32_e32 v55, 0xffff0000, v211
	v_pk_mul_f32 v[52:53], v[52:53], v[56:57]
	v_pk_mul_f32 v[48:49], v[48:49], v[54:55]
	v_cvt_pk_bf16_f32 v52, v52, v53
	v_cvt_pk_bf16_f32 v53, v48, v49
	v_lshl_add_u64 v[48:49], s[18:19], 0, v[50:51]
	v_lshl_add_u64 v[48:49], v[48:49], 0, v[126:127]
	global_store_dwordx2 v[48:49], v[52:53], off offset:3072
	s_nop 0
	s_nop 0
	v_pk_add_f32 v[42:43], v[42:43], v[156:157]
	s_nop 0
	v_mul_f32_e32 v42, 0xbfb8aa3b, v42
	v_mul_f32_e32 v43, 0xbfb8aa3b, v43
	v_exp_f32_e32 v42, v42
	v_exp_f32_e32 v43, v43
	v_pk_add_f32 v[44:45], v[44:45], v[158:159]
	v_add_f32_e32 v42, 1.0, v42
	v_add_f32_e32 v43, 1.0, v43
	v_rcp_f32_e32 v42, v42
	v_rcp_f32_e32 v43, v43
	s_nop 0
	v_lshlrev_b32_e32 v52, 16, v212
	v_and_b32_e32 v53, 0xffff0000, v212
	v_pk_mul_f32 v[42:43], v[42:43], v[52:53]
	v_lshlrev_b32_e32 v50, 16, v213
	v_cvt_pk_bf16_f32 v42, v42, v43
	v_mul_f32_e32 v43, 0xbfb8aa3b, v44
	v_exp_f32_e32 v43, v43
	v_and_b32_e32 v51, 0xffff0000, v213
	v_add_f32_e32 v43, 1.0, v43
	v_rcp_f32_e32 v44, v43
	v_mul_f32_e32 v43, 0xbfb8aa3b, v45
	v_exp_f32_e32 v43, v43
	s_nop 0
	v_add_f32_e32 v43, 1.0, v43
	v_rcp_f32_e32 v45, v43
	s_nop 0
	v_pk_mul_f32 v[44:45], v[44:45], v[50:51]
	s_nop 0
	v_cvt_pk_bf16_f32 v43, v44, v45
	global_store_dwordx2 v[48:49], v[42:43], off offset:3104
	s_nop 0
	s_nop 0
	v_pk_add_f32 v[38:39], v[38:39], v[160:161]
	s_nop 0
	v_mul_f32_e32 v38, 0xbfb8aa3b, v38
	v_mul_f32_e32 v39, 0xbfb8aa3b, v39
	v_exp_f32_e32 v38, v38
	v_exp_f32_e32 v39, v39
	v_pk_add_f32 v[40:41], v[40:41], v[162:163]
	v_add_f32_e32 v38, 1.0, v38
	v_add_f32_e32 v39, 1.0, v39
	v_rcp_f32_e32 v38, v38
	v_rcp_f32_e32 v39, v39
	s_nop 0
	v_lshlrev_b32_e32 v44, 16, v214
	v_and_b32_e32 v45, 0xffff0000, v214
	v_pk_mul_f32 v[38:39], v[38:39], v[44:45]
	v_lshlrev_b32_e32 v42, 16, v215
	v_cvt_pk_bf16_f32 v38, v38, v39
	v_mul_f32_e32 v39, 0xbfb8aa3b, v40
	v_exp_f32_e32 v39, v39
	v_and_b32_e32 v43, 0xffff0000, v215
	v_add_f32_e32 v39, 1.0, v39
	v_rcp_f32_e32 v40, v39
	v_mul_f32_e32 v39, 0xbfb8aa3b, v41
	v_exp_f32_e32 v39, v39
	s_nop 0
	v_add_f32_e32 v39, 1.0, v39
	v_rcp_f32_e32 v41, v39
	s_nop 0
	v_pk_mul_f32 v[40:41], v[40:41], v[42:43]
	s_nop 0
	v_cvt_pk_bf16_f32 v39, v40, v41
	global_store_dwordx2 v[48:49], v[38:39], off offset:3328
	s_nop 0
	s_nop 0
	v_pk_add_f32 v[34:35], v[34:35], v[164:165]
	s_nop 0
	v_mul_f32_e32 v34, 0xbfb8aa3b, v34
	v_mul_f32_e32 v35, 0xbfb8aa3b, v35
	v_exp_f32_e32 v34, v34
	v_exp_f32_e32 v35, v35
	v_pk_add_f32 v[36:37], v[36:37], v[166:167]
	v_add_f32_e32 v34, 1.0, v34
	v_add_f32_e32 v35, 1.0, v35
	v_rcp_f32_e32 v34, v34
	v_rcp_f32_e32 v35, v35
	s_nop 0
	v_lshlrev_b32_e32 v40, 16, v222
	v_and_b32_e32 v41, 0xffff0000, v222
	v_pk_mul_f32 v[34:35], v[34:35], v[40:41]
	v_lshlrev_b32_e32 v38, 16, v223
	v_cvt_pk_bf16_f32 v34, v34, v35
	v_mul_f32_e32 v35, 0xbfb8aa3b, v36
	v_exp_f32_e32 v35, v35
	v_and_b32_e32 v39, 0xffff0000, v223
	v_add_f32_e32 v35, 1.0, v35
	v_rcp_f32_e32 v36, v35
	v_mul_f32_e32 v35, 0xbfb8aa3b, v37
	v_exp_f32_e32 v35, v35
	s_nop 0
	v_add_f32_e32 v35, 1.0, v35
	v_rcp_f32_e32 v37, v35
	s_nop 0
	v_pk_mul_f32 v[36:37], v[36:37], v[38:39]
	s_nop 0
	v_cvt_pk_bf16_f32 v35, v36, v37
	global_store_dwordx2 v[48:49], v[34:35], off offset:3360
	s_nop 0
	v_add_u32_e32 v34, 0xa0, v138
	v_ashrrev_i32_e32 v35, 31, v34
	v_lshlrev_b64 v[40:41], 10, v[34:35]
	v_lshlrev_b64 v[34:35], 12, v[34:35]
	s_nop 0
	v_pk_add_f32 v[36:37], v[30:31], v[152:153]
	v_lshl_add_u64 v[30:31], s[28:29], 0, v[40:41]
	v_lshl_add_u64 v[30:31], v[30:31], 0, v[126:127]
	v_pk_add_f32 v[32:33], v[32:33], v[154:155]
	s_nop 0
	v_mul_f32_e32 v36, 0xbfb8aa3b, v36
	v_mul_f32_e32 v37, 0xbfb8aa3b, v37
	v_mul_f32_e32 v32, 0xbfb8aa3b, v32
	v_mul_f32_e32 v33, 0xbfb8aa3b, v33
	v_exp_f32_e32 v36, v36
	v_exp_f32_e32 v37, v37
	v_exp_f32_e32 v32, v32
	v_exp_f32_e32 v33, v33
	v_add_f32_e32 v36, 1.0, v36
	v_add_f32_e32 v37, 1.0, v37
	v_add_f32_e32 v32, 1.0, v32
	v_add_f32_e32 v33, 1.0, v33
	v_rcp_f32_e32 v36, v36
	v_rcp_f32_e32 v37, v37
	v_rcp_f32_e32 v32, v32
	v_rcp_f32_e32 v33, v33
	s_nop 0
	v_lshlrev_b32_e32 v40, 16, v224
	v_and_b32_e32 v41, 0xffff0000, v224
	v_lshlrev_b32_e32 v38, 16, v225
	v_and_b32_e32 v39, 0xffff0000, v225
	v_pk_mul_f32 v[36:37], v[36:37], v[40:41]
	v_pk_mul_f32 v[32:33], v[32:33], v[38:39]
	v_cvt_pk_bf16_f32 v36, v36, v37
	v_cvt_pk_bf16_f32 v37, v32, v33
	v_lshl_add_u64 v[32:33], s[18:19], 0, v[34:35]
	v_lshl_add_u64 v[32:33], v[32:33], 0, v[126:127]
	global_store_dwordx2 v[32:33], v[36:37], off offset:3072
	s_nop 0
	s_nop 0
	v_pk_add_f32 v[22:23], v[22:23], v[156:157]
	s_nop 0
	v_mul_f32_e32 v22, 0xbfb8aa3b, v22
	v_mul_f32_e32 v23, 0xbfb8aa3b, v23
	v_exp_f32_e32 v22, v22
	v_exp_f32_e32 v23, v23
	v_pk_add_f32 v[24:25], v[24:25], v[158:159]
	v_add_f32_e32 v22, 1.0, v22
	v_add_f32_e32 v23, 1.0, v23
	v_rcp_f32_e32 v22, v22
	v_rcp_f32_e32 v23, v23
	s_nop 0
	v_lshlrev_b32_e32 v36, 16, v228
	v_and_b32_e32 v37, 0xffff0000, v228
	v_pk_mul_f32 v[22:23], v[22:23], v[36:37]
	v_lshlrev_b32_e32 v34, 16, v229
	v_cvt_pk_bf16_f32 v22, v22, v23
	v_mul_f32_e32 v23, 0xbfb8aa3b, v24
	v_exp_f32_e32 v23, v23
	v_and_b32_e32 v35, 0xffff0000, v229
	v_add_f32_e32 v23, 1.0, v23
	v_rcp_f32_e32 v24, v23
	v_mul_f32_e32 v23, 0xbfb8aa3b, v25
	v_exp_f32_e32 v23, v23
	s_nop 0
	v_add_f32_e32 v23, 1.0, v23
	v_rcp_f32_e32 v25, v23
	s_nop 0
	v_pk_mul_f32 v[24:25], v[24:25], v[34:35]
	s_nop 0
	v_cvt_pk_bf16_f32 v23, v24, v25
	global_store_dwordx2 v[32:33], v[22:23], off offset:3104
	s_nop 0
	s_nop 0
	v_pk_add_f32 v[22:23], v[26:27], v[160:161]
	s_nop 0
	v_mul_f32_e32 v22, 0xbfb8aa3b, v22
	v_mul_f32_e32 v23, 0xbfb8aa3b, v23
	v_exp_f32_e32 v22, v22
	v_exp_f32_e32 v23, v23
	v_pk_add_f32 v[24:25], v[28:29], v[162:163]
	v_add_f32_e32 v22, 1.0, v22
	v_add_f32_e32 v23, 1.0, v23
	v_rcp_f32_e32 v22, v22
	v_rcp_f32_e32 v23, v23
	s_nop 0
	v_lshlrev_b32_e32 v28, 16, v232
	v_and_b32_e32 v29, 0xffff0000, v232
	v_pk_mul_f32 v[22:23], v[22:23], v[28:29]
	v_lshlrev_b32_e32 v26, 16, v233
	v_cvt_pk_bf16_f32 v22, v22, v23
	v_mul_f32_e32 v23, 0xbfb8aa3b, v24
	v_exp_f32_e32 v23, v23
	v_and_b32_e32 v27, 0xffff0000, v233
	v_add_f32_e32 v23, 1.0, v23
	v_rcp_f32_e32 v24, v23
	v_mul_f32_e32 v23, 0xbfb8aa3b, v25
	v_exp_f32_e32 v23, v23
	s_nop 0
	v_add_f32_e32 v23, 1.0, v23
	v_rcp_f32_e32 v25, v23
	s_nop 0
	v_pk_mul_f32 v[24:25], v[24:25], v[26:27]
	s_nop 0
	v_cvt_pk_bf16_f32 v23, v24, v25
	global_store_dwordx2 v[32:33], v[22:23], off offset:3328
	s_nop 0
	s_nop 0
	v_pk_add_f32 v[18:19], v[18:19], v[164:165]
	s_nop 0
	v_mul_f32_e32 v18, 0xbfb8aa3b, v18
	v_mul_f32_e32 v19, 0xbfb8aa3b, v19
	v_exp_f32_e32 v18, v18
	v_exp_f32_e32 v19, v19
	v_pk_add_f32 v[20:21], v[20:21], v[166:167]
	v_add_f32_e32 v18, 1.0, v18
	v_add_f32_e32 v19, 1.0, v19
	v_rcp_f32_e32 v18, v18
	v_rcp_f32_e32 v19, v19
	s_nop 0
	v_lshlrev_b32_e32 v24, 16, v234
	v_and_b32_e32 v25, 0xffff0000, v234
	v_pk_mul_f32 v[18:19], v[18:19], v[24:25]
	v_lshlrev_b32_e32 v22, 16, v235
	v_cvt_pk_bf16_f32 v18, v18, v19
	v_mul_f32_e32 v19, 0xbfb8aa3b, v20
	v_exp_f32_e32 v19, v19
	v_and_b32_e32 v23, 0xffff0000, v235
	v_add_f32_e32 v19, 1.0, v19
	v_rcp_f32_e32 v20, v19
	v_mul_f32_e32 v19, 0xbfb8aa3b, v21
	v_exp_f32_e32 v19, v19
	s_nop 0
	v_add_f32_e32 v19, 1.0, v19
	v_rcp_f32_e32 v21, v19
	s_nop 0
	v_pk_mul_f32 v[20:21], v[20:21], v[22:23]
	s_nop 0
	v_cvt_pk_bf16_f32 v19, v20, v21
	global_store_dwordx2 v[32:33], v[18:19], off offset:3360
	s_nop 0
	v_add_u32_e32 v18, 0xb0, v138
	v_ashrrev_i32_e32 v19, 31, v18
	v_lshlrev_b64 v[24:25], 10, v[18:19]
	v_lshlrev_b64 v[18:19], 12, v[18:19]
	s_nop 0
	v_pk_add_f32 v[20:21], v[14:15], v[152:153]
	v_lshl_add_u64 v[14:15], s[28:29], 0, v[24:25]
	v_lshl_add_u64 v[14:15], v[14:15], 0, v[126:127]
	v_pk_add_f32 v[16:17], v[16:17], v[154:155]
	s_waitcnt vmcnt(24)
	v_mul_f32_e32 v20, 0xbfb8aa3b, v20
	v_mul_f32_e32 v21, 0xbfb8aa3b, v21
	v_mul_f32_e32 v16, 0xbfb8aa3b, v16
	v_mul_f32_e32 v17, 0xbfb8aa3b, v17
	v_exp_f32_e32 v20, v20
	v_exp_f32_e32 v21, v21
	v_exp_f32_e32 v16, v16
	v_exp_f32_e32 v17, v17
	v_add_f32_e32 v20, 1.0, v20
	v_add_f32_e32 v21, 1.0, v21
	v_add_f32_e32 v16, 1.0, v16
	v_add_f32_e32 v17, 1.0, v17
	v_rcp_f32_e32 v20, v20
	v_rcp_f32_e32 v21, v21
	v_rcp_f32_e32 v16, v16
	v_rcp_f32_e32 v17, v17
	s_nop 0
	v_lshlrev_b32_e32 v24, 16, v168
	v_and_b32_e32 v25, 0xffff0000, v168
	v_lshlrev_b32_e32 v22, 16, v169
	v_and_b32_e32 v23, 0xffff0000, v169
	v_pk_mul_f32 v[20:21], v[20:21], v[24:25]
	v_pk_mul_f32 v[16:17], v[16:17], v[22:23]
	v_cvt_pk_bf16_f32 v20, v20, v21
	v_cvt_pk_bf16_f32 v21, v16, v17
	v_lshl_add_u64 v[16:17], s[18:19], 0, v[18:19]
	v_lshl_add_u64 v[16:17], v[16:17], 0, v[126:127]
	global_store_dwordx2 v[16:17], v[20:21], off offset:3072
	s_nop 0
	s_mov_b64 s[18:19], -1
	s_nop 0
	v_pk_add_f32 v[6:7], v[6:7], v[156:157]
	s_nop 0
	v_mul_f32_e32 v6, 0xbfb8aa3b, v6
	v_mul_f32_e32 v7, 0xbfb8aa3b, v7
	v_exp_f32_e32 v6, v6
	v_exp_f32_e32 v7, v7
	v_pk_add_f32 v[8:9], v[8:9], v[158:159]
	v_add_f32_e32 v6, 1.0, v6
	v_add_f32_e32 v7, 1.0, v7
	v_rcp_f32_e32 v6, v6
	v_rcp_f32_e32 v7, v7
	s_nop 0
	v_lshlrev_b32_e32 v20, 16, v170
	v_and_b32_e32 v21, 0xffff0000, v170
	v_pk_mul_f32 v[6:7], v[6:7], v[20:21]
	v_lshlrev_b32_e32 v18, 16, v171
	v_cvt_pk_bf16_f32 v6, v6, v7
	v_mul_f32_e32 v7, 0xbfb8aa3b, v8
	v_exp_f32_e32 v7, v7
	v_and_b32_e32 v19, 0xffff0000, v171
	v_add_f32_e32 v7, 1.0, v7
	v_rcp_f32_e32 v8, v7
	v_mul_f32_e32 v7, 0xbfb8aa3b, v9
	v_exp_f32_e32 v7, v7
	s_nop 0
	v_add_f32_e32 v7, 1.0, v7
	v_rcp_f32_e32 v9, v7
	s_nop 0
	v_pk_mul_f32 v[8:9], v[8:9], v[18:19]
	s_nop 0
	v_cvt_pk_bf16_f32 v7, v8, v9
	global_store_dwordx2 v[16:17], v[6:7], off offset:3104
	s_nop 0
	s_nop 0
	v_pk_add_f32 v[6:7], v[10:11], v[160:161]
	s_nop 0
	v_mul_f32_e32 v6, 0xbfb8aa3b, v6
	v_mul_f32_e32 v7, 0xbfb8aa3b, v7
	v_exp_f32_e32 v6, v6
	v_exp_f32_e32 v7, v7
	v_pk_add_f32 v[8:9], v[12:13], v[162:163]
	v_add_f32_e32 v6, 1.0, v6
	v_add_f32_e32 v7, 1.0, v7
	v_rcp_f32_e32 v6, v6
	v_rcp_f32_e32 v7, v7
	s_nop 0
	v_lshlrev_b32_e32 v12, 16, v172
	v_and_b32_e32 v13, 0xffff0000, v172
	v_pk_mul_f32 v[6:7], v[6:7], v[12:13]
	v_lshlrev_b32_e32 v10, 16, v173
	v_cvt_pk_bf16_f32 v6, v6, v7
	v_mul_f32_e32 v7, 0xbfb8aa3b, v8
	v_exp_f32_e32 v7, v7
	v_and_b32_e32 v11, 0xffff0000, v173
	v_add_f32_e32 v7, 1.0, v7
	v_rcp_f32_e32 v8, v7
	v_mul_f32_e32 v7, 0xbfb8aa3b, v9
	v_exp_f32_e32 v7, v7
	s_nop 0
	v_add_f32_e32 v7, 1.0, v7
	v_rcp_f32_e32 v9, v7
	s_nop 0
	v_pk_mul_f32 v[8:9], v[8:9], v[10:11]
	s_nop 0
	v_cvt_pk_bf16_f32 v7, v8, v9
	global_store_dwordx2 v[16:17], v[6:7], off offset:3328
	s_nop 0
	s_nop 0
	v_pk_add_f32 v[2:3], v[2:3], v[164:165]
	s_nop 0
	v_mul_f32_e32 v2, 0xbfb8aa3b, v2
	v_mul_f32_e32 v3, 0xbfb8aa3b, v3
	v_exp_f32_e32 v2, v2
	v_exp_f32_e32 v3, v3
	v_pk_add_f32 v[4:5], v[4:5], v[166:167]
	v_add_f32_e32 v2, 1.0, v2
	v_add_f32_e32 v3, 1.0, v3
	v_rcp_f32_e32 v2, v2
	v_rcp_f32_e32 v3, v3
	s_nop 0
	v_lshlrev_b32_e32 v8, 16, v174
	v_and_b32_e32 v9, 0xffff0000, v174
	v_pk_mul_f32 v[2:3], v[2:3], v[8:9]
	v_lshlrev_b32_e32 v6, 16, v175
	v_cvt_pk_bf16_f32 v2, v2, v3
	v_mul_f32_e32 v3, 0xbfb8aa3b, v4
	v_exp_f32_e32 v3, v3
	v_and_b32_e32 v7, 0xffff0000, v175
	v_add_f32_e32 v3, 1.0, v3
	v_rcp_f32_e32 v4, v3
	v_mul_f32_e32 v3, 0xbfb8aa3b, v5
	v_exp_f32_e32 v3, v3
	s_nop 0
	v_add_f32_e32 v3, 1.0, v3
	v_rcp_f32_e32 v5, v3
	s_nop 0
	v_pk_mul_f32 v[4:5], v[4:5], v[6:7]
	s_nop 0
	v_cvt_pk_bf16_f32 v3, v4, v5
	global_store_dwordx2 v[16:17], v[2:3], off offset:3360
	s_cbranch_vccnz .LBB0_2724
	s_andn2_b64 vcc, exec, s[6:7]
	s_cbranch_vccnz .LBB0_2723
	s_barrier
